# EpiQ: the 8 row groups' sum-of-squares loads issued together at the first group (were load + vmcnt(0) on the next line, per group)
# speedup vs baseline: 1.0076x; 1.0017x over previous
.LBB0_781:
	s_lshl_b32 s8, s8, 8
	v_mbcnt_lo_u32_b32 v140, -1, 0
	v_mbcnt_hi_u32_b32 v140, -1, v140
	s_add_i32 s8, s8, s30
	v_and_b32_e32 v163, 15, v140
	v_or_b32_e32 v148, s8, v163
	v_ashrrev_i32_e32 v149, 31, v148
	v_lshl_add_u64 v[128:129], v[148:149], 4, s[12:13]
	v_mov_b64_e32 v[250:251], v[128:129]
	global_load_dwordx4 v[182:185], v[250:251], off offset:256
	global_load_dwordx4 v[186:189], v[250:251], off offset:512
	global_load_dwordx4 v[190:193], v[250:251], off offset:768
	global_load_dwordx4 v[194:197], v[250:251], off offset:2048
	global_load_dwordx4 v[198:201], v[250:251], off offset:2304
	global_load_dwordx4 v[202:205], v[250:251], off offset:2560
	global_load_dwordx4 v[206:209], v[250:251], off offset:2816
	global_load_dwordx4 v[128:131], v[128:129], off
	s_lshl_b32 s4, s6, 8
	v_ashrrev_i32_e32 v140, 1, v140
	s_or_b32 s4, s4, s31
	v_and_b32_e32 v140, -8, v140
	v_add_u32_e32 v150, s4, v140
	v_mul_hi_i32 v140, v150, s39
	v_lshrrev_b32_e32 v146, 31, v140
	v_ashrrev_i32_e32 v140, 4, v140
	v_add_u32_e32 v162, v140, v146
	v_mad_u64_u32 v[146:147], s[4:5], v162, s53, v[150:151]
	s_waitcnt vmcnt(0)
	v_mov_b32_e32 v142, v129
	v_mov_b32_e32 v143, v130
	v_mov_b32_e32 v129, v131
	v_pk_add_f32 v[128:129], v[142:143], v[128:129]
	s_nop 0
	v_add_f32_e32 v128, v128, v129
	v_fmamk_f32 v128, v128, 0x3b800000, v161
	v_mul_f32_e32 v129, 0x4b800000, v128
	v_cmp_gt_f32_e32 vcc, s43, v128
	s_nop 1
	v_cndmask_b32_e32 v128, v128, v129, vcc
	v_rsq_f32_e32 v128, v128
	s_nop 0
	v_mul_f32_e32 v129, 0x45800000, v128
	v_cndmask_b32_e32 v152, v128, v129, vcc
	v_pk_mul_f32 v[156:157], v[126:127], v[152:153] op_sel_hi:[1,0]
	v_pk_mul_f32 v[128:129], v[124:125], v[152:153] op_sel_hi:[1,0]
	v_pk_mul_f32 v[154:155], v[122:123], v[152:153] op_sel_hi:[1,0]
	v_pk_mul_f32 v[124:125], v[120:121], v[152:153] op_sel_hi:[1,0]
	v_cmp_gt_i32_e32 vcc, 64, v146
	s_and_saveexec_b64 s[4:5], vcc
	s_xor_b64 s[4:5], exec, s[4:5]
	s_cbranch_execz .LBB0_783
	v_cvt_pk_bf16_f32 v120, v128, v129
	v_cvt_pk_bf16_f32 v121, v156, v157
	v_cvt_pk_bf16_f32 v122, v124, v125
	v_cvt_pk_bf16_f32 v123, v154, v155

.LBB0_789:
	s_or_b64 exec, exec, s[6:7]
	v_add_u32_e32 v116, s9, v149
	v_ashrrev_i32_e32 v117, 31, v116
	v_lshlrev_b64 v[116:117], 12, v[116:117]
	v_or_b32_e32 v119, v116, v154
	v_mov_b64_e32 v[120:121], s[74:75]
	v_mad_u64_u32 v[120:121], s[6:7], v119, s29, v[120:121]
	v_mad_i32_i24 v121, v117, s29, v121
	v_ashrrev_i32_e32 v125, 31, v124
	v_lshl_add_u64 v[120:121], v[124:125], 1, v[120:121]
	global_store_dwordx4 v[120:121], v[112:115], off
	v_or_b32_e32 v120, 16, v148
	v_ashrrev_i32_e32 v121, 31, v120
	v_lshl_add_u64 v[112:113], v[120:121], 4, s[12:13]
	v_mov_b64_e32 v[112:113], v[182:183]
	v_mov_b64_e32 v[114:115], v[184:185]
	v_mov_b32_e32 v122, v113
	v_mov_b32_e32 v123, v114
	v_mov_b32_e32 v113, v115
	v_pk_add_f32 v[112:113], v[122:123], v[112:113]
	s_nop 0
	v_add_f32_e32 v112, v112, v113
	v_fmamk_f32 v112, v112, 0x3b800000, v161
	v_mul_f32_e32 v113, 0x4b800000, v112
	v_cmp_gt_f32_e64 s[6:7], s43, v112
	s_nop 1
	v_cndmask_b32_e64 v112, v112, v113, s[6:7]
	v_rsq_f32_e32 v112, v112
	s_nop 0
	v_mul_f32_e32 v113, 0x45800000, v112
	v_cndmask_b32_e64 v122, v112, v113, s[6:7]
	v_pk_mul_f32 v[130:131], v[110:111], v[122:123] op_sel_hi:[1,0]
	v_pk_mul_f32 v[112:113], v[108:109], v[122:123] op_sel_hi:[1,0]
	v_pk_mul_f32 v[128:129], v[106:107], v[122:123] op_sel_hi:[1,0]
	v_pk_mul_f32 v[104:105], v[104:105], v[122:123] op_sel_hi:[1,0]
	s_and_saveexec_b64 s[6:7], vcc
	s_xor_b64 s[6:7], exec, s[6:7]
	s_cbranch_execz .LBB0_791
	v_cvt_pk_bf16_f32 v108, v112, v113
	v_cvt_pk_bf16_f32 v109, v130, v131
	v_cvt_pk_bf16_f32 v110, v104, v105
	v_cvt_pk_bf16_f32 v111, v128, v129

.LBB0_797:
	s_or_b64 exec, exec, s[6:7]
	v_or_b32_e32 v98, v116, v112
	v_mov_b64_e32 v[96:97], s[74:75]
	v_mad_u64_u32 v[96:97], s[6:7], v98, s29, v[96:97]
	v_mad_i32_i24 v97, v117, s29, v97
	v_lshl_add_u64 v[96:97], v[124:125], 1, v[96:97]
	global_store_dwordx4 v[96:97], v[100:103], off
	s_nop 1
	v_or_b32_e32 v100, 32, v148
	v_ashrrev_i32_e32 v101, 31, v100
	v_lshl_add_u64 v[96:97], v[100:101], 4, s[12:13]
	v_mov_b64_e32 v[96:97], v[186:187]
	v_mov_b64_e32 v[98:99], v[188:189]
	v_mov_b32_e32 v102, v97
	v_mov_b32_e32 v103, v98
	v_mov_b32_e32 v97, v99
	v_pk_add_f32 v[96:97], v[102:103], v[96:97]
	s_nop 0
	v_add_f32_e32 v96, v96, v97
	v_fmamk_f32 v96, v96, 0x3b800000, v161
	v_mul_f32_e32 v97, 0x4b800000, v96
	v_cmp_gt_f32_e64 s[6:7], s43, v96
	s_nop 1
	v_cndmask_b32_e64 v96, v96, v97, s[6:7]
	v_rsq_f32_e32 v96, v96
	s_nop 0
	v_mul_f32_e32 v97, 0x45800000, v96
	v_cndmask_b32_e64 v102, v96, v97, s[6:7]
	v_pk_mul_f32 v[106:107], v[94:95], v[102:103] op_sel_hi:[1,0]
	v_pk_mul_f32 v[96:97], v[92:93], v[102:103] op_sel_hi:[1,0]
	v_pk_mul_f32 v[104:105], v[90:91], v[102:103] op_sel_hi:[1,0]
	v_pk_mul_f32 v[88:89], v[88:89], v[102:103] op_sel_hi:[1,0]
	s_and_saveexec_b64 s[6:7], vcc
	s_xor_b64 s[6:7], exec, s[6:7]
	s_cbranch_execz .LBB0_799
	v_cvt_pk_bf16_f32 v92, v96, v97
	v_cvt_pk_bf16_f32 v93, v106, v107
	v_cvt_pk_bf16_f32 v94, v88, v89
	v_cvt_pk_bf16_f32 v95, v104, v105

.LBB0_805:
	s_or_b64 exec, exec, s[6:7]
	v_or_b32_e32 v82, v116, v96
	v_mov_b64_e32 v[80:81], s[74:75]
	v_mad_u64_u32 v[80:81], s[6:7], v82, s29, v[80:81]
	v_mad_i32_i24 v81, v117, s29, v81
	v_lshl_add_u64 v[80:81], v[124:125], 1, v[80:81]
	global_store_dwordx4 v[80:81], v[84:87], off
	s_nop 1
	v_or_b32_e32 v84, 48, v148
	v_ashrrev_i32_e32 v85, 31, v84
	v_lshl_add_u64 v[80:81], v[84:85], 4, s[12:13]
	v_mov_b64_e32 v[80:81], v[190:191]
	v_mov_b64_e32 v[82:83], v[192:193]
	v_mov_b32_e32 v86, v81
	v_mov_b32_e32 v87, v82
	v_mov_b32_e32 v81, v83
	v_pk_add_f32 v[80:81], v[86:87], v[80:81]
	s_nop 0
	v_add_f32_e32 v80, v80, v81
	v_fmamk_f32 v80, v80, 0x3b800000, v161
	v_mul_f32_e32 v81, 0x4b800000, v80
	v_cmp_gt_f32_e64 s[6:7], s43, v80
	s_nop 1
	v_cndmask_b32_e64 v80, v80, v81, s[6:7]
	v_rsq_f32_e32 v80, v80
	s_nop 0
	v_mul_f32_e32 v81, 0x45800000, v80
	v_cndmask_b32_e64 v86, v80, v81, s[6:7]
	v_pk_mul_f32 v[90:91], v[78:79], v[86:87] op_sel_hi:[1,0]
	v_pk_mul_f32 v[80:81], v[76:77], v[86:87] op_sel_hi:[1,0]
	v_pk_mul_f32 v[88:89], v[74:75], v[86:87] op_sel_hi:[1,0]
	v_pk_mul_f32 v[72:73], v[72:73], v[86:87] op_sel_hi:[1,0]
	s_and_saveexec_b64 s[6:7], vcc
	s_xor_b64 s[6:7], exec, s[6:7]
	s_cbranch_execz .LBB0_807
	v_cvt_pk_bf16_f32 v76, v80, v81
	v_cvt_pk_bf16_f32 v77, v90, v91
	v_cvt_pk_bf16_f32 v78, v72, v73
	v_cvt_pk_bf16_f32 v79, v88, v89

.LBB0_813:
	s_or_b64 exec, exec, s[6:7]
	v_or_b32_e32 v66, v116, v80
	v_mov_b64_e32 v[64:65], s[74:75]
	v_mad_u64_u32 v[64:65], s[6:7], v66, s29, v[64:65]
	v_mad_i32_i24 v65, v117, s29, v65
	v_lshl_add_u64 v[64:65], v[124:125], 1, v[64:65]
	s_addk_i32 s8, 0x80
	global_store_dwordx4 v[64:65], v[68:71], off
	s_nop 1
	v_or_b32_e32 v68, s8, v163
	v_ashrrev_i32_e32 v69, 31, v68
	v_lshl_add_u64 v[64:65], v[68:69], 4, s[12:13]
	v_mov_b64_e32 v[64:65], v[194:195]
	v_mov_b64_e32 v[66:67], v[196:197]
	v_mov_b32_e32 v70, v65
	v_mov_b32_e32 v71, v66
	v_mov_b32_e32 v65, v67
	v_pk_add_f32 v[64:65], v[70:71], v[64:65]
	s_nop 0
	v_add_f32_e32 v64, v64, v65
	v_fmamk_f32 v64, v64, 0x3b800000, v161
	v_mul_f32_e32 v65, 0x4b800000, v64
	v_cmp_gt_f32_e64 s[6:7], s43, v64
	s_nop 1
	v_cndmask_b32_e64 v64, v64, v65, s[6:7]
	v_rsq_f32_e32 v64, v64
	s_nop 0
	v_mul_f32_e32 v65, 0x45800000, v64
	v_cndmask_b32_e64 v70, v64, v65, s[6:7]
	v_pk_mul_f32 v[72:73], v[62:63], v[70:71] op_sel_hi:[1,0]
	v_pk_mul_f32 v[64:65], v[60:61], v[70:71] op_sel_hi:[1,0]
	v_pk_mul_f32 v[66:67], v[58:59], v[70:71] op_sel_hi:[1,0]
	v_pk_mul_f32 v[60:61], v[56:57], v[70:71] op_sel_hi:[1,0]
	s_and_saveexec_b64 s[6:7], vcc
	s_xor_b64 s[6:7], exec, s[6:7]
	s_cbranch_execz .LBB0_815
	v_cvt_pk_bf16_f32 v56, v64, v65
	v_cvt_pk_bf16_f32 v57, v72, v73
	v_cvt_pk_bf16_f32 v58, v60, v61
	v_cvt_pk_bf16_f32 v59, v66, v67

.LBB0_821:
	s_or_b64 exec, exec, s[6:7]
	v_add_u32_e32 v52, s8, v149
	v_ashrrev_i32_e32 v53, 31, v52
	v_lshlrev_b64 v[52:53], 12, v[52:53]
	v_or_b32_e32 v56, v52, v66
	v_mov_b64_e32 v[54:55], s[74:75]
	v_mad_u64_u32 v[54:55], s[6:7], v56, s29, v[54:55]
	v_mad_i32_i24 v55, v53, s29, v55
	v_lshl_add_u64 v[54:55], v[124:125], 1, v[54:55]
	global_store_dwordx4 v[54:55], v[48:51], off
	v_or_b32_e32 v54, 16, v68
	v_ashrrev_i32_e32 v55, 31, v54
	v_lshl_add_u64 v[48:49], v[54:55], 4, s[12:13]
	v_mov_b64_e32 v[48:49], v[198:199]
	v_mov_b64_e32 v[50:51], v[200:201]
	v_mov_b32_e32 v56, v49
	v_mov_b32_e32 v57, v50
	v_mov_b32_e32 v49, v51
	v_pk_add_f32 v[48:49], v[56:57], v[48:49]
	s_nop 0
	v_add_f32_e32 v48, v48, v49
	v_fmamk_f32 v48, v48, 0x3b800000, v161
	v_mul_f32_e32 v49, 0x4b800000, v48
	v_cmp_gt_f32_e64 s[6:7], s43, v48
	s_nop 1
	v_cndmask_b32_e64 v48, v48, v49, s[6:7]
	v_rsq_f32_e32 v48, v48
	s_nop 0
	v_mul_f32_e32 v49, 0x45800000, v48
	v_cndmask_b32_e64 v56, v48, v49, s[6:7]
	v_pk_mul_f32 v[62:63], v[46:47], v[56:57] op_sel_hi:[1,0]
	v_pk_mul_f32 v[48:49], v[44:45], v[56:57] op_sel_hi:[1,0]
	v_pk_mul_f32 v[58:59], v[42:43], v[56:57] op_sel_hi:[1,0]
	v_pk_mul_f32 v[40:41], v[40:41], v[56:57] op_sel_hi:[1,0]
	s_and_saveexec_b64 s[6:7], vcc
	s_xor_b64 s[6:7], exec, s[6:7]
	s_cbranch_execz .LBB0_823
	v_cvt_pk_bf16_f32 v44, v48, v49
	v_cvt_pk_bf16_f32 v45, v62, v63
	v_cvt_pk_bf16_f32 v46, v40, v41
	v_cvt_pk_bf16_f32 v47, v58, v59

.LBB0_829:
	s_or_b64 exec, exec, s[6:7]
	v_or_b32_e32 v34, v52, v48
	v_mov_b64_e32 v[32:33], s[74:75]
	v_mad_u64_u32 v[32:33], s[6:7], v34, s29, v[32:33]
	v_mad_i32_i24 v33, v53, s29, v33
	v_lshl_add_u64 v[32:33], v[124:125], 1, v[32:33]
	global_store_dwordx4 v[32:33], v[36:39], off
	s_nop 1
	v_or_b32_e32 v36, 32, v68
	v_ashrrev_i32_e32 v37, 31, v36
	v_lshl_add_u64 v[32:33], v[36:37], 4, s[12:13]
	v_mov_b64_e32 v[32:33], v[202:203]
	v_mov_b64_e32 v[34:35], v[204:205]
	v_mov_b32_e32 v38, v33
	v_mov_b32_e32 v39, v34
	v_mov_b32_e32 v33, v35
	v_pk_add_f32 v[32:33], v[38:39], v[32:33]
	s_nop 0
	v_add_f32_e32 v32, v32, v33
	v_fmamk_f32 v32, v32, 0x3b800000, v161
	v_mul_f32_e32 v33, 0x4b800000, v32
	v_cmp_gt_f32_e64 s[6:7], s43, v32
	s_nop 1
	v_cndmask_b32_e64 v32, v32, v33, s[6:7]
	v_rsq_f32_e32 v32, v32
	s_nop 0
	v_mul_f32_e32 v33, 0x45800000, v32
	v_cndmask_b32_e64 v38, v32, v33, s[6:7]
	v_pk_mul_f32 v[42:43], v[30:31], v[38:39] op_sel_hi:[1,0]
	v_pk_mul_f32 v[32:33], v[28:29], v[38:39] op_sel_hi:[1,0]
	v_pk_mul_f32 v[40:41], v[26:27], v[38:39] op_sel_hi:[1,0]
	v_pk_mul_f32 v[24:25], v[24:25], v[38:39] op_sel_hi:[1,0]
	s_and_saveexec_b64 s[6:7], vcc
	s_xor_b64 s[6:7], exec, s[6:7]
	s_cbranch_execz .LBB0_831
	v_cvt_pk_bf16_f32 v28, v32, v33
	v_cvt_pk_bf16_f32 v29, v42, v43
	v_cvt_pk_bf16_f32 v30, v24, v25
	v_cvt_pk_bf16_f32 v31, v40, v41

.LBB0_837:
	s_or_b64 exec, exec, s[6:7]
	v_or_b32_e32 v18, v52, v32
	v_mov_b64_e32 v[16:17], s[74:75]
	v_mad_u64_u32 v[16:17], s[6:7], v18, s29, v[16:17]
	v_mad_i32_i24 v17, v53, s29, v17
	v_lshl_add_u64 v[16:17], v[124:125], 1, v[16:17]
	global_store_dwordx4 v[16:17], v[20:23], off
	s_nop 1
	v_or_b32_e32 v20, 48, v68
	v_ashrrev_i32_e32 v21, 31, v20
	v_lshl_add_u64 v[16:17], v[20:21], 4, s[12:13]
	v_mov_b64_e32 v[16:17], v[206:207]
	v_mov_b64_e32 v[18:19], v[208:209]
	v_mov_b32_e32 v22, v17
	v_mov_b32_e32 v23, v18
	v_mov_b32_e32 v17, v19
	v_pk_add_f32 v[16:17], v[22:23], v[16:17]
	s_nop 0
	v_add_f32_e32 v16, v16, v17
	v_fmamk_f32 v16, v16, 0x3b800000, v161
	v_mul_f32_e32 v17, 0x4b800000, v16
	v_cmp_gt_f32_e64 s[6:7], s43, v16
	s_nop 1
	v_cndmask_b32_e64 v16, v16, v17, s[6:7]
	v_rsq_f32_e32 v16, v16
	s_nop 0
	v_mul_f32_e32 v17, 0x45800000, v16
	v_cndmask_b32_e64 v22, v16, v17, s[6:7]
	v_pk_mul_f32 v[24:25], v[14:15], v[22:23] op_sel_hi:[1,0]
	v_pk_mul_f32 v[16:17], v[12:13], v[22:23] op_sel_hi:[1,0]
	v_pk_mul_f32 v[18:19], v[10:11], v[22:23] op_sel_hi:[1,0]
	v_pk_mul_f32 v[12:13], v[8:9], v[22:23] op_sel_hi:[1,0]
	s_and_saveexec_b64 s[6:7], vcc
	s_xor_b64 s[6:7], exec, s[6:7]
	s_cbranch_execz .LBB0_839
	v_cvt_pk_bf16_f32 v8, v16, v17
	v_cvt_pk_bf16_f32 v9, v24, v25
	v_cvt_pk_bf16_f32 v10, v12, v13
	v_cvt_pk_bf16_f32 v11, v18, v19
